# k18 + GLA scan loop: prefetch loads issued before the staging publish barrier (same edit as the mLSTM loop)
# baseline (speedup 1.0000x reference)
.LBB0_1890:
	s_or_b64 exec, exec, s[44:45]
	s_add_i32 s87, s86, 1
	s_cmpk_eq_i32 s86, 0x43
	s_cbranch_scc1 .LBB0_1899
	s_cmp_lt_u32 s86, 3
	s_cselect_b32 s28, 3, 0x47
	s_add_i32 s40, s28, s85
	s_and_b64 s[28:29], s[0:1], exec
	s_cselect_b32 s44, s87, s40
	s_add_i32 s40, s44, s80
	s_lshl_b64 s[28:29], s[40:41], 13
	s_lshl_b64 s[46:47], s[40:41], 14
	s_add_u32 s88, s31, s46
	s_addc_u32 s89, s30, s47
	s_add_u32 s46, s52, s46
	v_lshl_add_u64 v[4:5], v[54:55], 0, s[28:29]
	s_addc_u32 s47, s51, s47
	global_load_dwordx4 v[6:9], v[4:5], off
	v_lshl_add_u64 v[4:5], s[88:89], 0, v[48:49]
	global_load_dwordx4 v[10:13], v[4:5], off
	v_lshl_add_u64 v[4:5], s[46:47], 0, v[46:47]
	global_load_dwordx4 v[14:17], v[4:5], off
	v_lshl_add_u64 v[4:5], s[88:89], 0, v[50:51]
	global_load_dwordx4 v[18:21], v[4:5], off
	v_lshl_add_u64 v[4:5], s[46:47], 0, v[52:53]
	global_load_dwordx4 v[26:29], v[4:5], off
	s_and_saveexec_b64 s[46:47], vcc
	s_cbranch_execz .LBB0_1893
	s_ashr_i32 s45, s44, 31
	s_lshl_b64 s[28:29], s[44:45], 15
	v_lshl_add_u64 v[4:5], v[56:57], 0, s[28:29]
	global_load_dwordx4 v[22:25], v[4:5], off

.LBB0_1895:
	s_or_b64 exec, exec, s[44:45]
	s_waitcnt lgkmcnt(0)
	s_barrier
	v_add_u32_e32 v2, v79, v81
	s_and_saveexec_b64 s[28:29], s[8:9]
	s_xor_b64 s[44:45], exec, s[28:29]
	s_cbranch_execnz .LBB0_1900

.LBB0_1899:
	s_waitcnt lgkmcnt(0)
	s_barrier
	v_add_u32_e32 v2, v79, v81
	s_and_saveexec_b64 s[28:29], s[8:9]
	s_xor_b64 s[44:45], exec, s[28:29]
	s_cbranch_execz .LBB0_1896
